# v54 + hyena filter set-up: the eight reversed-tap loads issued together (were eight load->wait round trips per order)
# speedup vs baseline: 1.0081x; 1.0011x over previous
.LBB0_255:
	s_lshl_b32 s12, s14, 9
	s_add_i32 s10, s12, s20
	s_ashr_i32 s11, s10, 31
	s_lshl_b64 s[10:11], s[10:11], 2
	s_waitcnt lgkmcnt(0)
	s_add_u32 s10, s82, s10
	s_addc_u32 s11, s83, s11
	s_ashr_i32 s13, s12, 31
	global_load_dword v6, v1, s[10:11]
	s_add_i32 s16, s70, s12
	s_lshl_b64 s[10:11], s[12:13], 2
	s_add_u32 s18, s74, s10
	s_addc_u32 s19, s75, s11
	s_add_u32 s10, s78, s10
	global_load_dword v54, v1, s[18:19] offset:2048
	global_load_dword v56, v212, s[18:19]
	global_load_dword v58, v211, s[18:19] offset:2048
	s_addc_u32 s11, s79, s11
	global_load_dword v60, v1, s[10:11] offset:2048
	s_movk_i32 s52, 0x1000
	s_lshl_b32 s10, s52, 1
	v_cvt_f32_i32_e32 v0, s10
	s_ashr_i32 s13, s52, 3
	v_cmp_gt_i32_e64 s[48:49], s13, v36
	v_div_scale_f32 v7, s[10:11], v0, v0, 1.0
	v_rcp_f32_e32 v28, v7
	s_nop 0
	v_fma_f32 v29, -v7, v28, 1.0
	v_fmac_f32_e32 v28, v29, v28
	v_div_scale_f32 v29, vcc, 1.0, v0, 1.0
	v_mul_f32_e32 v30, v29, v28
	v_fma_f32 v31, -v7, v30, v29
	v_fmac_f32_e32 v30, v31, v28
	v_fma_f32 v7, -v7, v30, v29
	v_div_fmas_f32 v7, v7, v28, v30
	v_div_fixup_f32 v7, v7, v0, 1.0
	v_mov_b32_e32 v28, 0
	s_and_saveexec_b64 s[10:11], s[48:49]
	s_cbranch_execz .LBB0_273
	s_lshl_b32 s13, s14, 10
	s_add_i32 s13, s13, s2
	v_mov_b32_e32 v0, 0x4400
	v_mad_i64_i32 v[32:33], s[14:15], s13, v0, v[46:47]
	global_load_dwordx4 v[28:31], v[32:33], off offset:16
	s_nop 0
	global_load_dwordx4 v[32:35], v[32:33], off
	s_add_i32 s12, s16, s12
	s_mul_hi_i32 s13, s12, 0x4400
	s_mulk_i32 s12, 0x4400
	s_add_u32 s12, s94, s12
	s_addc_u32 s13, s95, s13
	s_nop 0
	s_nop 0
	s_nop 0
	s_nop 0
	v_sub_u32_e32 v236, s52, v44
	v_ashrrev_i32_e32 v237, 31, v236
	v_lshl_add_u64 v[236:237], v[236:237], 2, s[12:13]
	global_load_dword v238, v[236:237], off
	global_load_dword v239, v[236:237], off offset:-4
	global_load_dword v240, v[236:237], off offset:-8
	global_load_dword v241, v[236:237], off offset:-12
	global_load_dword v242, v[236:237], off offset:-16
	global_load_dword v243, v[236:237], off offset:-20
	global_load_dword v244, v[236:237], off offset:-24
	global_load_dword v245, v[236:237], off offset:-28
	s_add_i32 s14, s52, -1
	v_cvt_f32_i32_e32 v0, s14
	v_and_b32_e32 v55, 0x7fffffff, v37
	v_div_scale_f32 v57, s[14:15], v0, v0, v55
	v_rcp_f32_e32 v59, v57
	v_div_scale_f32 v55, vcc, v55, v0, v55
	v_fma_f32 v61, -v57, v59, 1.0
	v_fmac_f32_e32 v59, v61, v59
	v_mul_f32_e32 v61, v55, v59
	v_fma_f32 v62, -v57, v61, v55
	v_fmac_f32_e32 v61, v62, v59
	v_fma_f32 v55, -v57, v61, v55
	v_div_fmas_f32 v55, v55, v59, v61
	v_div_fixup_f32 v55, v55, v0, |v37|
	v_mov_b32_e32 v61, 0
	v_mov_b32_e32 v59, 0
	s_and_saveexec_b64 s[14:15], s[44:45]
	s_cbranch_execz .LBB0_258
	v_sub_u32_e32 v62, s52, v44
	v_ashrrev_i32_e32 v63, 31, v62
	v_lshl_add_u64 v[64:65], v[62:63], 2, s[12:13]
	v_cvt_f32_i32_e32 v57, v62
	v_mul_f32_e32 v57, v55, v57
	v_mul_f32_e32 v57, 0xbfb8aa3b, v57
	v_exp_f32_e32 v57, v57
	s_waitcnt vmcnt(0)
	v_mov_b32_e32 v0, v238
	v_mul_f32_e32 v59, v57, v0
.LBB0_258:
	s_or_b64 exec, exec, s[14:15]
	v_mul_f32_e32 v0, v55, v138
	v_mul_f32_e32 v0, 0xbfb8aa3b, v0
	v_exp_f32_e32 v62, v0
	v_mul_f32_e32 v0, v7, v138
	v_cos_f32_e32 v64, v0
	v_sin_f32_e32 v65, v0
	s_waitcnt vmcnt(0)
	v_fma_f32 v0, v62, v32, v59
	ds_write_b64 v139, v[0:1]
	v_add_u32_e32 v0, s52, v48
	v_ashrrev_i32_e32 v57, 4, v0
	v_fma_f32 v66, v62, v32, -v59
	v_lshlrev_b32_e32 v63, 3, v57
	v_lshlrev_b32_e32 v57, 3, v0
	v_pk_mul_f32 v[64:65], v[64:65], v[66:67] op_sel_hi:[1,0] neg_hi:[0,1]
	v_add3_u32 v0, 0, v63, v57
	ds_write_b64 v0, v[64:65]
	s_and_saveexec_b64 s[14:15], s[46:47]
	s_cbranch_execz .LBB0_260
	s_ashr_i32 s17, s52, 31
	v_mov_b32_e32 v0, s17
	v_sub_co_u32_e32 v64, vcc, s52, v44
	v_sub_u32_e32 v61, s52, v140
	s_nop 0
	v_subb_co_u32_e32 v65, vcc, v0, v45, vcc
	v_lshl_add_u64 v[64:65], v[64:65], 2, s[12:13]
	v_cvt_f32_i32_e32 v61, v61
	v_mul_f32_e32 v61, v55, v61
	v_mul_f32_e32 v61, 0xbfb8aa3b, v61
	v_exp_f32_e32 v61, v61
	s_waitcnt vmcnt(0)
	v_mov_b32_e32 v0, v239
	v_mul_f32_e32 v61, v61, v0
.LBB0_260:
	s_or_b64 exec, exec, s[14:15]
	v_mul_f32_e32 v0, v55, v141
	v_mul_f32_e32 v0, 0xbfb8aa3b, v0
	v_exp_f32_e32 v64, v0
	v_mul_f32_e32 v0, v7, v141
	v_cos_f32_e32 v66, v0
	v_sin_f32_e32 v67, v0
	v_fma_f32 v0, v64, v33, v61
	ds_write_b64 v139, v[0:1] offset:8
	v_add_u32_e32 v0, s52, v140
	v_ashrrev_i32_e32 v0, 4, v0
	v_fma_f32 v68, v64, v33, -v61
	v_lshlrev_b32_e32 v0, 3, v0
	v_pk_mul_f32 v[66:67], v[66:67], v[68:69] op_sel_hi:[1,0] neg_hi:[0,1]
	v_add3_u32 v0, 0, v0, v57
	ds_write_b64 v0, v[66:67] offset:8
	v_mov_b32_e32 v65, 0
	v_mov_b32_e32 v66, 0
	s_and_saveexec_b64 s[14:15], s[46:47]
	s_cbranch_execz .LBB0_262
	s_ashr_i32 s17, s52, 31
	v_mov_b32_e32 v0, s17
	v_sub_co_u32_e32 v66, vcc, s52, v44
	v_sub_u32_e32 v63, s52, v142
	s_nop 0
	v_subb_co_u32_e32 v67, vcc, v0, v45, vcc
	v_lshl_add_u64 v[66:67], v[66:67], 2, s[12:13]
	v_cvt_f32_i32_e32 v63, v63
	v_mul_f32_e32 v63, v55, v63
	v_mul_f32_e32 v63, 0xbfb8aa3b, v63
	v_exp_f32_e32 v63, v63
	s_waitcnt vmcnt(0)
	v_mov_b32_e32 v0, v240
	v_mul_f32_e32 v66, v63, v0
.LBB0_262:
	s_or_b64 exec, exec, s[14:15]
	v_mul_f32_e32 v0, v55, v143
	v_mul_f32_e32 v0, 0xbfb8aa3b, v0
	v_exp_f32_e32 v67, v0
	v_mul_f32_e32 v0, v7, v143
	v_cos_f32_e32 v68, v0
	v_sin_f32_e32 v69, v0
	v_fma_f32 v0, v67, v34, v66
	ds_write_b64 v139, v[0:1] offset:16
	v_add_u32_e32 v0, s52, v142
	v_ashrrev_i32_e32 v0, 4, v0
	v_fma_f32 v70, v67, v34, -v66
	v_lshlrev_b32_e32 v0, 3, v0
	v_pk_mul_f32 v[68:69], v[68:69], v[70:71] op_sel_hi:[1,0] neg_hi:[0,1]
	v_add3_u32 v0, 0, v0, v57
	ds_write_b64 v0, v[68:69] offset:16
	s_and_saveexec_b64 s[14:15], s[46:47]
	s_cbranch_execz .LBB0_264
	s_ashr_i32 s17, s52, 31
	v_mov_b32_e32 v0, s17
	v_sub_co_u32_e32 v68, vcc, s52, v44
	v_sub_u32_e32 v63, s52, v144
	s_nop 0
	v_subb_co_u32_e32 v69, vcc, v0, v45, vcc
	v_lshl_add_u64 v[68:69], v[68:69], 2, s[12:13]
	v_cvt_f32_i32_e32 v63, v63
	v_mul_f32_e32 v63, v55, v63
	v_mul_f32_e32 v63, 0xbfb8aa3b, v63
	v_exp_f32_e32 v63, v63
	s_waitcnt vmcnt(0)
	v_mov_b32_e32 v0, v241
	v_mul_f32_e32 v65, v63, v0
.LBB0_264:
	s_or_b64 exec, exec, s[14:15]
	v_mul_f32_e32 v0, v55, v145
	v_mul_f32_e32 v0, 0xbfb8aa3b, v0
	v_exp_f32_e32 v68, v0
	v_mul_f32_e32 v0, v7, v145
	v_cos_f32_e32 v70, v0
	v_sin_f32_e32 v71, v0
	v_fma_f32 v0, v68, v35, v65
	ds_write_b64 v139, v[0:1] offset:24
	v_add_u32_e32 v0, s52, v144
	v_ashrrev_i32_e32 v0, 4, v0
	v_fma_f32 v72, v68, v35, -v65
	v_lshlrev_b32_e32 v0, 3, v0
	v_pk_mul_f32 v[70:71], v[70:71], v[72:73] op_sel_hi:[1,0] neg_hi:[0,1]
	v_add3_u32 v0, 0, v0, v57
	ds_write_b64 v0, v[70:71] offset:24
	v_mov_b32_e32 v69, 0
	v_mov_b32_e32 v70, 0
	s_and_saveexec_b64 s[14:15], s[46:47]
	s_cbranch_execz .LBB0_266
	s_ashr_i32 s17, s52, 31
	v_mov_b32_e32 v0, s17
	v_sub_co_u32_e32 v70, vcc, s52, v44
	v_sub_u32_e32 v63, s52, v146
	s_nop 0
	v_subb_co_u32_e32 v71, vcc, v0, v45, vcc
	v_lshl_add_u64 v[70:71], v[70:71], 2, s[12:13]
	v_cvt_f32_i32_e32 v63, v63
	v_mul_f32_e32 v63, v55, v63
	v_mul_f32_e32 v63, 0xbfb8aa3b, v63
	v_exp_f32_e32 v63, v63
	s_waitcnt vmcnt(0)
	v_mov_b32_e32 v0, v242
	v_mul_f32_e32 v70, v63, v0
.LBB0_266:
	s_or_b64 exec, exec, s[14:15]
	v_mul_f32_e32 v0, v55, v147
	v_mul_f32_e32 v0, 0xbfb8aa3b, v0
	v_exp_f32_e32 v71, v0
	v_mul_f32_e32 v0, v7, v147
	v_cos_f32_e32 v72, v0
	v_sin_f32_e32 v73, v0
	v_fma_f32 v0, v71, v28, v70
	ds_write_b64 v139, v[0:1] offset:32
	v_add_u32_e32 v0, s52, v146
	v_ashrrev_i32_e32 v0, 4, v0
	v_fma_f32 v74, v71, v28, -v70
	v_lshlrev_b32_e32 v0, 3, v0
	v_pk_mul_f32 v[72:73], v[72:73], v[74:75] op_sel_hi:[1,0] neg_hi:[0,1]
	v_add3_u32 v0, 0, v0, v57
	ds_write_b64 v0, v[72:73] offset:32
	s_and_saveexec_b64 s[14:15], s[46:47]
	s_cbranch_execz .LBB0_268
	s_ashr_i32 s17, s52, 31
	v_mov_b32_e32 v0, s17
	v_sub_co_u32_e32 v72, vcc, s52, v44
	v_sub_u32_e32 v63, s52, v148
	s_nop 0
	v_subb_co_u32_e32 v73, vcc, v0, v45, vcc
	v_lshl_add_u64 v[72:73], v[72:73], 2, s[12:13]
	v_cvt_f32_i32_e32 v63, v63
	v_mul_f32_e32 v63, v55, v63
	v_mul_f32_e32 v63, 0xbfb8aa3b, v63
	v_exp_f32_e32 v63, v63
	s_waitcnt vmcnt(0)
	v_mov_b32_e32 v0, v243
	v_mul_f32_e32 v69, v63, v0
.LBB0_268:
	s_or_b64 exec, exec, s[14:15]
	v_mul_f32_e32 v0, v55, v149
	v_mul_f32_e32 v0, 0xbfb8aa3b, v0
	v_exp_f32_e32 v72, v0
	v_mul_f32_e32 v0, v7, v149
	v_cos_f32_e32 v74, v0
	v_sin_f32_e32 v75, v0
	v_fma_f32 v0, v72, v29, v69
	ds_write_b64 v139, v[0:1] offset:40
	v_add_u32_e32 v0, s52, v148
	v_ashrrev_i32_e32 v0, 4, v0
	v_fma_f32 v76, v72, v29, -v69
	v_lshlrev_b32_e32 v0, 3, v0
	v_pk_mul_f32 v[74:75], v[74:75], v[76:77] op_sel_hi:[1,0] neg_hi:[0,1]
	v_add3_u32 v0, 0, v0, v57
	v_mov_b32_e32 v63, 0
	v_mov_b32_e32 v73, 0
	ds_write_b64 v0, v[74:75] offset:40
	s_and_saveexec_b64 s[14:15], s[46:47]
	s_cbranch_execz .LBB0_270
	s_ashr_i32 s17, s52, 31
	v_mov_b32_e32 v0, s17
	v_sub_co_u32_e32 v74, vcc, s52, v44
	v_sub_u32_e32 v73, s52, v150
	s_nop 0
	v_subb_co_u32_e32 v75, vcc, v0, v45, vcc
	v_lshl_add_u64 v[74:75], v[74:75], 2, s[12:13]
	v_cvt_f32_i32_e32 v73, v73
	v_mul_f32_e32 v73, v55, v73
	v_mul_f32_e32 v73, 0xbfb8aa3b, v73
	v_exp_f32_e32 v73, v73
	s_waitcnt vmcnt(0)
	v_mov_b32_e32 v0, v244
	v_mul_f32_e32 v73, v73, v0
.LBB0_270:
	s_or_b64 exec, exec, s[14:15]
	v_mul_f32_e32 v0, v55, v151
	v_mul_f32_e32 v0, 0xbfb8aa3b, v0
	v_exp_f32_e32 v74, v0
	v_mul_f32_e32 v0, v7, v151
	v_cos_f32_e32 v76, v0
	v_sin_f32_e32 v77, v0
	v_fma_f32 v0, v74, v30, v73
	ds_write_b64 v139, v[0:1] offset:48
	v_add_u32_e32 v0, s52, v150
	v_ashrrev_i32_e32 v0, 4, v0
	v_fma_f32 v78, v74, v30, -v73
	v_lshlrev_b32_e32 v0, 3, v0
	v_pk_mul_f32 v[76:77], v[76:77], v[78:79] op_sel_hi:[1,0] neg_hi:[0,1]
	v_add3_u32 v0, 0, v0, v57
	ds_write_b64 v0, v[76:77] offset:48
	s_and_saveexec_b64 s[14:15], s[46:47]
	s_cbranch_execz .LBB0_272
	s_ashr_i32 s17, s52, 31
	v_mov_b32_e32 v0, s17
	v_sub_co_u32_e32 v76, vcc, s52, v44
	v_sub_u32_e32 v63, s52, v152
	s_nop 0
	v_subb_co_u32_e32 v77, vcc, v0, v45, vcc
	v_lshl_add_u64 v[76:77], v[76:77], 2, s[12:13]
	v_cvt_f32_i32_e32 v63, v63
	v_mul_f32_e32 v63, v55, v63
	v_mul_f32_e32 v63, 0xbfb8aa3b, v63
	v_exp_f32_e32 v63, v63
	s_waitcnt vmcnt(0)
	v_mov_b32_e32 v0, v245
	v_mul_f32_e32 v63, v63, v0
